# GEMM_out main loop: the 8 MFMAs of k-substep 1 carried across the loop-back barrier and issued between the next iteration's LDS-DMA groups; B/A1 fragments read right after the barrier
# speedup vs baseline: 1.0389x; 1.0066x over previous
; DI void gemm_tile(const Params& p, const GemmJob& j, int mt, int nt, char* smem) {
;     ...
;   auto glds = [&](int kt, int stage) {
;     char* sb = smem + stage * GSTAGE;
;     const unsigned ko = j.amode ? (unsigned)((kt >> 1) * j.lda + (kt & 1) * 32) : (unsigned)(kt * 32);
; #pragma unroll
;     for (int q = 0; q < 2; ++q) {
;       const int ch = q * 4 + wid;
;       const bf16_t* src = j.bblk ? j.Bt + ((size_t)kt * j.bblk + n0 + 16 * ch + rl) * 32 + c8s : j.Bt + (size_t)(n0 + 16 * ch + rl) * j.K + kt * 32 + c8s;
;       __builtin_amdgcn_global_load_lds((gptr_t)src, (lptr_t)(sb + ch * 1024), 16, 0, 0);
;     }
; #pragma unroll
;     for (int q = 0; q < 4; ++q) {
;       const int ch = q * 4 + wid;
;       const bf16_t* src = j.ablk ? j.A + ((size_t)kt * j.ablk + t0 + 16 * ch + rl) * 32 + c8s : j.A + a_rowoff(j, t0 + 16 * ch + rl) + ko + c8s;
;       __builtin_amdgcn_global_load_lds((gptr_t)src, (lptr_t)(sb + 8192 + ch * 1024), 16, 0, 0);
;     }
;   };
;   const int fr = (r >> 2) & 3; const int o0 = (h ^ fr) * 16;
;   __syncthreads();
;   glds(0, 0);
;   if (nk > 1) glds(1, 1);
.LBB0_885:
	s_waitcnt vmcnt(10)
	v_mov_b32_e32 v134, v167
	s_lshl_b32 s6, s1, 8
	v_readfirstlane_b32 s31, v134
	s_ashr_i32 s38, s31, 6
	s_bfe_u32 s29, s1, 0x30002
	s_and_b32 s40, s6, 0xffffe300
	s_lshl_b32 s6, s38, 4
	s_and_b32 s33, s38, 1
	s_lshl_b32 s30, s29, 7
	s_or_b32 s28, s40, s70
	s_ashr_i32 s7, s6, 31
	s_add_u32 s10, s6, s30
	v_lshrrev_b32_e32 v10, 4, v134
	s_waitcnt lgkmcnt(0)
	v_bfe_u32 v2, v134, 2, 4
	s_addc_u32 s11, s7, 0
	s_add_i32 s36, s38, 4
	v_xor_b32_e32 v0, v10, v134
	v_or_b32_e32 v4, s10, v2
	v_mov_b32_e32 v5, s11
	s_lshl_b32 s55, s38, 10
	s_lshl_b32 s10, s36, 4
	v_lshlrev_b64 v[4:5], 6, v[4:5]
	v_lshlrev_b32_e32 v0, 4, v0
	s_add_i32 s41, s55, 0
	s_ashr_i32 s11, s10, 31
	s_waitcnt lgkmcnt(0)
	v_lshl_add_u64 v[4:5], s[2:3], 0, v[4:5]
	v_and_b32_e32 v0, 48, v0
	s_add_u32 s37, s10, s30
	v_lshl_add_u64 v[4:5], v[4:5], 0, v[0:1]
	s_mov_b32 m0, s41
	s_addc_u32 s39, s11, 0
	s_barrier
	global_load_lds_dwordx4 v[4:5], off
	v_or_b32_e32 v4, s37, v2
	v_mov_b32_e32 v5, s39
	s_lshl_b32 s58, s36, 10
	v_lshlrev_b64 v[4:5], 6, v[4:5]
	s_add_i32 s42, s58, 0
	s_ashr_i32 s43, s28, 31
	v_lshl_add_u64 v[4:5], s[2:3], 0, v[4:5]
	s_add_u32 s36, s6, s28
	v_lshl_add_u64 v[4:5], v[4:5], 0, v[0:1]
	s_mov_b32 m0, s42
	s_addc_u32 s37, s7, s43
	global_load_lds_dwordx4 v[4:5], off
	v_or_b32_e32 v4, s36, v2
	v_mov_b32_e32 v5, s37
	v_readlane_b32 s12, v230, 51
	v_lshlrev_b64 v[4:5], 6, v[4:5]
	v_readlane_b32 s14, v230, 53
	v_readlane_b32 s15, v230, 54
	s_add_i32 m0, s41, 0x2000
	s_add_u32 s36, s10, s28
	v_lshl_add_u64 v[4:5], s[14:15], 0, v[4:5]
	v_lshl_add_u64 v[4:5], v[4:5], 0, v[0:1]
	s_addc_u32 s37, s11, s43
	s_add_i32 s39, s38, 8
	global_load_lds_dwordx4 v[4:5], off
	v_or_b32_e32 v4, s36, v2
	v_mov_b32_e32 v5, s37
	s_lshl_b32 s36, s39, 4
	v_lshlrev_b64 v[4:5], 6, v[4:5]
	s_add_i32 m0, s42, 0x2000
	s_ashr_i32 s37, s36, 31
	v_lshl_add_u64 v[4:5], s[14:15], 0, v[4:5]
	s_add_u32 s44, s36, s28
	v_lshl_add_u64 v[4:5], v[4:5], 0, v[0:1]
	s_addc_u32 s45, s37, s43
	global_load_lds_dwordx4 v[4:5], off
	v_mov_b32_e32 v5, s45
	s_lshl_b32 s62, s39, 10
	s_add_i32 s45, s38, 12
	v_or_b32_e32 v4, s44, v2
	s_add_i32 s44, s62, 0
	s_lshl_b32 s38, s45, 4
	v_lshlrev_b64 v[4:5], 6, v[4:5]
	s_add_i32 m0, s44, 0x2000
	s_ashr_i32 s39, s38, 31
	v_lshl_add_u64 v[4:5], s[14:15], 0, v[4:5]
	s_add_u32 s46, s38, s28
	v_lshl_add_u64 v[4:5], v[4:5], 0, v[0:1]
	s_addc_u32 s47, s39, s43
	global_load_lds_dwordx4 v[4:5], off
	v_or_b32_e32 v4, s46, v2
	v_mov_b32_e32 v5, s47
	v_lshlrev_b64 v[4:5], 6, v[4:5]
	s_lshl_b32 s63, s45, 10
	v_lshl_add_u64 v[4:5], s[14:15], 0, v[4:5]
	s_add_i32 s45, s63, 0
	v_lshl_add_u64 v[4:5], v[4:5], 0, v[0:1]
	s_add_i32 m0, s45, 0x2000
	v_and_b32_e32 v136, 31, v134
	global_load_lds_dwordx4 v[4:5], off
	v_or_b32_e32 v4, s30, v2
	v_mov_b32_e32 v5, v1
	v_lshl_add_u64 v[6:7], v[4:5], 0, s[6:7]
	v_lshlrev_b64 v[6:7], 6, v[6:7]
	v_lshl_add_u64 v[6:7], s[2:3], 0, v[6:7]
	v_lshl_add_u64 v[6:7], v[6:7], 0, v[0:1]
	v_lshl_add_u64 v[6:7], v[6:7], 0, s[56:57]
	s_add_i32 m0, s41, 0x6000
	v_bfe_u32 v135, v134, 5, 1
	global_load_lds_dwordx4 v[6:7], off
	v_lshl_add_u64 v[6:7], s[10:11], 0, v[4:5]
	v_lshlrev_b64 v[6:7], 6, v[6:7]
	v_lshl_add_u64 v[6:7], s[2:3], 0, v[6:7]
	v_lshl_add_u64 v[6:7], v[6:7], 0, v[0:1]
	v_lshl_add_u64 v[6:7], v[6:7], 0, s[56:57]
	s_add_i32 m0, s42, 0x6000
	v_lshrrev_b32_e32 v3, 2, v134
	global_load_lds_dwordx4 v[6:7], off
	v_or_b32_e32 v6, s28, v2
	v_mov_b32_e32 v7, s43
	v_lshl_add_u64 v[8:9], v[6:7], 0, s[6:7]
	v_lshlrev_b64 v[8:9], 6, v[8:9]
	v_lshl_add_u64 v[8:9], s[14:15], 0, v[8:9]
	v_lshl_add_u64 v[8:9], v[8:9], 0, v[0:1]
	v_lshl_add_u64 v[8:9], v[8:9], 0, s[88:89]
	s_add_i32 m0, s41, 0x8000
	v_bitop3_b32 v3, v135, v3, 3 bitop3:0x78
	global_load_lds_dwordx4 v[8:9], off
	v_lshl_add_u64 v[8:9], v[6:7], 0, s[10:11]
	v_lshlrev_b64 v[8:9], 6, v[8:9]
	v_lshl_add_u64 v[8:9], s[14:15], 0, v[8:9]
	v_lshl_add_u64 v[8:9], v[8:9], 0, v[0:1]
	v_lshl_add_u64 v[8:9], v[8:9], 0, s[88:89]
	s_add_i32 m0, s42, 0x8000
	s_and_b32 s10, s31, 0x3ffff80
	global_load_lds_dwordx4 v[8:9], off
	v_lshl_add_u64 v[8:9], v[6:7], 0, s[36:37]
	v_lshlrev_b64 v[8:9], 6, v[8:9]
	v_lshl_add_u64 v[6:7], v[6:7], 0, s[38:39]
	v_lshl_add_u64 v[8:9], s[14:15], 0, v[8:9]
	v_lshlrev_b64 v[6:7], 6, v[6:7]
	v_lshl_add_u64 v[8:9], v[8:9], 0, v[0:1]
	v_lshl_add_u64 v[6:7], s[14:15], 0, v[6:7]
	v_lshl_add_u64 v[8:9], v[8:9], 0, s[88:89]
	s_add_i32 m0, s44, 0x8000
	v_lshl_add_u64 v[6:7], v[6:7], 0, v[0:1]
	global_load_lds_dwordx4 v[8:9], off
	v_lshl_add_u64 v[6:7], v[6:7], 0, s[88:89]
	s_add_i32 m0, s45, 0x8000
	v_or_b32_e32 v0, s10, v136
	global_load_lds_dwordx4 v[6:7], off
	s_add_i32 s10, s70, s40
	s_ashr_i32 s11, s10, 31
	s_add_u32 s10, s10, s6
	v_lshlrev_b32_e32 v137, 4, v3
	v_mov_b32_e32 v3, v1
	s_addc_u32 s11, s11, s7
	v_lshl_add_u64 v[2:3], s[10:11], 0, v[2:3]
	v_lshlrev_b64 v[2:3], 6, v[2:3]
	v_lshl_add_u64 v[130:131], s[14:15], 0, v[2:3]
	v_lshl_add_u64 v[2:3], s[6:7], 0, v[4:5]
	v_lshlrev_b32_e32 v6, 6, v136
	s_waitcnt vmcnt(0)
; DI void gemm_tile(const Params& p, const GemmJob& j, int mt, int nt, char* smem) {
;     ...
;   const int t0 = mt * 256, n0 = nt * 128;
;   const int rl = lane >> 2, c8s = ((lane & 3) ^ ((lane >> 4) & 3)) * 8;
;   const int nk = j.K >> 5;
;   f32x16 acc[2][4];
; #pragma unroll
;   for (int a = 0; a < 2; ++a)
; #pragma unroll
;     for (int b = 0; b < 4; ++b)
; #pragma unroll
;       for (int i = 0; i < 16; ++i) acc[a][b][i] = 0.f;
;   auto glds = [&](int kt, int stage) {
;     char* sb = smem + stage * GSTAGE;
;     const unsigned ko = j.amode ? (unsigned)((kt >> 1) * j.lda + (kt & 1) * 32) : (unsigned)(kt * 32);
; #pragma unroll
;     for (int q = 0; q < 2; ++q) {
;       const int ch = q * 4 + wid;
;       const bf16_t* src = j.bblk ? j.Bt + ((size_t)kt * j.bblk + n0 + 16 * ch + rl) * 32 + c8s : j.Bt + (size_t)(n0 + 16 * ch + rl) * j.K + kt * 32 + c8s;
;       __builtin_amdgcn_global_load_lds((gptr_t)src, (lptr_t)(sb + ch * 1024), 16, 0, 0);
;     }
; #pragma unroll
;     for (int q = 0; q < 4; ++q) {
;       const int ch = q * 4 + wid;
;       const bf16_t* src = j.ablk ? j.A + ((size_t)kt * j.ablk + t0 + 16 * ch + rl) * 32 + c8s : j.A + a_rowoff(j, t0 + 16 * ch + rl) + ko + c8s;
;       __builtin_amdgcn_global_load_lds((gptr_t)src, (lptr_t)(sb + 8192 + ch * 1024), 16, 0, 0);
;     }
;   };
;   const int fr = (r >> 2) & 3; const int o0 = (h ^ fr) * 16;
;   __syncthreads();
;   glds(0, 0);
;   if (nk > 1) glds(1, 1);
;   int st = 0, st2 = 2;
	v_lshlrev_b32_e32 v139, 6, v0
	v_bitop3_b32 v0, v10, 3, v134 bitop3:0x48
	v_lshlrev_b64 v[2:3], 6, v[2:3]
	v_mov_b32_e32 v82, 0
	s_mov_b32 s54, 2
	v_xor_b32_e32 v138, 32, v137
	v_lshl_or_b32 v140, s33, 12, v6
	v_lshlrev_b32_e32 v0, 4, v0
	v_lshl_add_u64 v[132:133], s[2:3], 0, v[2:3]
	s_mov_b32 s6, 0
	s_mov_b32 s7, 30
	v_mov_b32_e32 v83, v82
	v_mov_b32_e32 v84, v82
	v_mov_b32_e32 v85, v82
	v_mov_b32_e32 v86, v82
	v_mov_b32_e32 v87, v82
	v_mov_b32_e32 v88, v82
	v_mov_b32_e32 v89, v82
	v_mov_b32_e32 v90, v82
	v_mov_b32_e32 v91, v82
	v_mov_b32_e32 v92, v82
	v_mov_b32_e32 v93, v82
	v_mov_b32_e32 v94, v82
	v_mov_b32_e32 v95, v82
	v_mov_b32_e32 v96, v82
	v_mov_b32_e32 v97, v82
	v_mov_b32_e32 v50, v82
	v_mov_b32_e32 v51, v82
	v_mov_b32_e32 v52, v82
	v_mov_b32_e32 v53, v82
	v_mov_b32_e32 v54, v82
	v_mov_b32_e32 v55, v82
	v_mov_b32_e32 v56, v82
	v_mov_b32_e32 v57, v82
	v_mov_b32_e32 v58, v82
	v_mov_b32_e32 v59, v82
	v_mov_b32_e32 v60, v82
	v_mov_b32_e32 v61, v82
	v_mov_b32_e32 v62, v82
	v_mov_b32_e32 v63, v82
	v_mov_b32_e32 v64, v82
	v_mov_b32_e32 v65, v82
	v_mov_b32_e32 v18, v82
	v_mov_b32_e32 v19, v82
	v_mov_b32_e32 v20, v82
	v_mov_b32_e32 v21, v82
	v_mov_b32_e32 v22, v82
	v_mov_b32_e32 v23, v82
	v_mov_b32_e32 v24, v82
	v_mov_b32_e32 v25, v82
	v_mov_b32_e32 v26, v82
	v_mov_b32_e32 v27, v82
	v_mov_b32_e32 v28, v82
	v_mov_b32_e32 v29, v82
	v_mov_b32_e32 v30, v82
	v_mov_b32_e32 v31, v82
	v_mov_b32_e32 v32, v82
	v_mov_b32_e32 v33, v82
	v_mov_b32_e32 v2, v82
	v_mov_b32_e32 v3, v82
	v_mov_b32_e32 v4, v82
	v_mov_b32_e32 v5, v82
	v_mov_b32_e32 v6, v82
	v_mov_b32_e32 v7, v82
	v_mov_b32_e32 v8, v82
	v_mov_b32_e32 v9, v82
	v_mov_b32_e32 v10, v82
	v_mov_b32_e32 v11, v82
	v_mov_b32_e32 v12, v82
	v_mov_b32_e32 v13, v82
	v_mov_b32_e32 v14, v82
	v_mov_b32_e32 v15, v82
	v_mov_b32_e32 v16, v82
	v_mov_b32_e32 v17, v82
	v_mov_b32_e32 v114, v82
	v_mov_b32_e32 v115, v82
	v_mov_b32_e32 v116, v82
	v_mov_b32_e32 v117, v82
	v_mov_b32_e32 v118, v82
	v_mov_b32_e32 v119, v82
	v_mov_b32_e32 v120, v82
	v_mov_b32_e32 v121, v82
	v_mov_b32_e32 v122, v82
	v_mov_b32_e32 v123, v82
	v_mov_b32_e32 v124, v82
	v_mov_b32_e32 v125, v82
	v_mov_b32_e32 v126, v82
	v_mov_b32_e32 v127, v82
	v_mov_b32_e32 v128, v82
	v_mov_b32_e32 v129, v82
	v_mov_b32_e32 v98, v82
	v_mov_b32_e32 v99, v82
	v_mov_b32_e32 v100, v82
	v_mov_b32_e32 v101, v82
	v_mov_b32_e32 v102, v82
	v_mov_b32_e32 v103, v82
	v_mov_b32_e32 v104, v82
	v_mov_b32_e32 v105, v82
	v_mov_b32_e32 v106, v82
	v_mov_b32_e32 v107, v82
	v_mov_b32_e32 v108, v82
	v_mov_b32_e32 v109, v82
	v_mov_b32_e32 v110, v82
	v_mov_b32_e32 v111, v82
	v_mov_b32_e32 v112, v82
	v_mov_b32_e32 v113, v82
	v_mov_b32_e32 v66, v82
	v_mov_b32_e32 v67, v82
	v_mov_b32_e32 v68, v82
	v_mov_b32_e32 v69, v82
	v_mov_b32_e32 v70, v82
	v_mov_b32_e32 v71, v82
	v_mov_b32_e32 v72, v82
	v_mov_b32_e32 v73, v82
	v_mov_b32_e32 v74, v82
	v_mov_b32_e32 v75, v82
	v_mov_b32_e32 v76, v82
	v_mov_b32_e32 v77, v82
	v_mov_b32_e32 v78, v82
	v_mov_b32_e32 v79, v82
	v_mov_b32_e32 v80, v82
	v_mov_b32_e32 v81, v82
	v_mov_b32_e32 v34, v82
	v_mov_b32_e32 v35, v82
	v_mov_b32_e32 v36, v82
	v_mov_b32_e32 v37, v82
	v_mov_b32_e32 v38, v82
	v_mov_b32_e32 v39, v82
	v_mov_b32_e32 v40, v82
	v_mov_b32_e32 v41, v82
	v_mov_b32_e32 v42, v82
	v_mov_b32_e32 v43, v82
	v_mov_b32_e32 v44, v82
	v_mov_b32_e32 v45, v82
	v_mov_b32_e32 v46, v82
	v_mov_b32_e32 v47, v82
	v_mov_b32_e32 v48, v82
	v_mov_b32_e32 v49, v82
	v_readlane_b32 s13, v230, 52
	v_readlane_b32 s16, v230, 55
	v_readlane_b32 s17, v230, 56
	v_readlane_b32 s18, v230, 57
	v_readlane_b32 s19, v230, 58
	v_readlane_b32 s20, v230, 59
	v_readlane_b32 s21, v230, 60
	v_readlane_b32 s22, v230, 61
	v_readlane_b32 s23, v230, 62
	v_readlane_b32 s24, v230, 63
	v_readlane_b32 s25, v229, 0
	v_readlane_b32 s26, v229, 1
	v_readlane_b32 s27, v229, 2
	v_mov_b32_e32 v232, 0
	v_mov_b32_e32 v233, 0
	v_mov_b32_e32 v234, 0
	v_mov_b32_e32 v235, 0
	v_mov_b32_e32 v236, 0
	v_mov_b32_e32 v237, 0
	v_mov_b32_e32 v238, 0
	v_mov_b32_e32 v239, 0
	v_mov_b32_e32 v240, 0
	v_mov_b32_e32 v241, 0
	v_mov_b32_e32 v242, 0
	v_mov_b32_e32 v243, 0
	v_mov_b32_e32 v244, 0
	v_mov_b32_e32 v245, 0
	v_mov_b32_e32 v246, 0
	v_mov_b32_e32 v247, 0
	v_mov_b32_e32 v248, 0
	v_mov_b32_e32 v249, 0
	v_mov_b32_e32 v250, 0
	v_mov_b32_e32 v251, 0
	v_mov_b32_e32 v252, 0
	v_mov_b32_e32 v253, 0
	v_mov_b32_e32 v254, 0
	v_mov_b32_e32 v255, 0
; DI f32x16 mfma32(bf16x8 a, bf16x8 b, f32x16 c) { return __builtin_amdgcn_mfma_f32_32x32x16_bf16(a, b, c, 0, 0, 0); }
; #define RAW_BARRIER() do { asm volatile("s_waitcnt lgkmcnt(0)" ::: "memory"); __builtin_amdgcn_s_barrier(); } while (0)
; DI void gemm_tile(const Params& p, const GemmJob& j, int mt, int nt, char* smem) {
;     ...
;   for (int kt = 0; kt < nk; ++kt) {
;     if (kt + 1 < nk) asm volatile("s_waitcnt vmcnt(6)" ::: "memory"); else asm volatile("s_waitcnt vmcnt(0)" ::: "memory");
;     RAW_BARRIER();
;     if (kt + 2 < nk) glds(kt + 2, st2);
;     const char* sb = smem + st * GSTAGE;
; #pragma unroll
;     for (int ks = 0; ks < 2; ++ks) {
;       const int off = ks ? (o0 ^ 32) : o0;
;       bf16x8 wf[2], xf[4];
; #pragma unroll
;       for (int a = 0; a < 2; ++a) wf[a] = *(const bf16x8*)(sb + (64 * wn + 32 * a + r) * 64 + off);
; #pragma unroll
;       for (int b = 0; b < 4; ++b) xf[b] = *(const bf16x8*)(sb + 8192 + (128 * wt + 32 * b + r) * 64 + off);
; #pragma unroll
;       for (int a = 0; a < 2; ++a)
; #pragma unroll
;         for (int b = 0; b < 4; ++b) acc[a][b] = mfma32(wf[a], xf[b], acc[a][b]);
;     }
;     st = (st == 2) ? 0 : st + 1; st2 = (st2 == 2) ? 0 : st2 + 1;
;   }
.LBB0_886:
	s_mul_i32 s10, s54, 0x6000
	s_add_i32 s36, s10, 0
	v_lshl_add_u64 v[142:143], v[132:133], 0, v[0:1]
	s_mov_b64 s[10:11], 0x20000
	s_add_i32 s37, s36, s55
	s_waitcnt vmcnt(6)
	v_lshl_add_u64 v[144:145], v[142:143], 0, s[10:11]
	s_mov_b32 m0, s37
	s_mov_b64 s[10:11], 0x21000
	s_add_i32 s38, s36, s58
	s_waitcnt lgkmcnt(0)
	s_mul_i32 s100, s6, 0x6000
	v_add_u32_e32 v141, s100, v137
	v_add_u32_e32 v146, v141, v140
	v_add_u32_e32 v141, v141, v139
	s_barrier
	ds_read_b128 v[150:153], v141 offset:8192
	ds_read_b128 v[154:157], v141 offset:10240
	ds_read_b128 v[158:161], v141 offset:12288
	ds_read_b128 v[162:165], v141 offset:14336
	ds_read_b128 v[146:149], v146 offset:2048
	global_load_lds_dwordx4 v[144:145], off
	v_mfma_f32_32x32x16_bf16 v[82:97], v[232:235], v[240:243], v[82:97]
	v_lshl_add_u64 v[142:143], v[142:143], 0, s[10:11]
	s_mov_b32 m0, s38
	s_mov_b64 s[10:11], 0x401000
	global_load_lds_dwordx4 v[142:143], off
	v_mfma_f32_32x32x16_bf16 v[50:65], v[232:235], v[244:247], v[50:65]
	v_lshl_add_u64 v[142:143], v[130:131], 0, v[0:1]
	v_lshl_add_u64 v[144:145], v[142:143], 0, s[92:93]
	s_add_i32 m0, s37, 0x2000
	v_lshl_add_u64 v[130:131], v[130:131], 0, s[88:89]
	global_load_lds_dwordx4 v[144:145], off
	v_mfma_f32_32x32x16_bf16 v[18:33], v[232:235], v[248:251], v[18:33]
	v_lshl_add_u64 v[144:145], v[142:143], 0, s[10:11]
	s_add_i32 m0, s38, 0x2000
	s_add_i32 s10, s36, s62
	global_load_lds_dwordx4 v[144:145], off
	v_mfma_f32_32x32x16_bf16 v[2:17], v[232:235], v[252:255], v[2:17]
	v_lshl_add_u64 v[144:145], v[142:143], 0, s[84:85]
	s_add_i32 m0, s10, 0x2000
	s_add_i32 s10, s36, s63
	global_load_lds_dwordx4 v[144:145], off
	v_mfma_f32_32x32x16_bf16 v[114:129], v[236:239], v[240:243], v[114:129]
	v_lshl_add_u64 v[142:143], v[142:143], 0, s[52:53]
	s_add_i32 m0, s10, 0x2000
	s_mul_i32 s10, s6, 0x6000
	global_load_lds_dwordx4 v[142:143], off
	v_mfma_f32_32x32x16_bf16 v[98:113], v[236:239], v[244:247], v[98:113]
	v_mfma_f32_32x32x16_bf16 v[66:81], v[236:239], v[248:251], v[66:81]
	v_mfma_f32_32x32x16_bf16 v[34:49], v[236:239], v[252:255], v[34:49]
	v_add_u32_e32 v142, s100, v137
	v_add_u32_e32 v142, v142, v140
	ds_read_b128 v[142:145], v142
	v_add_u32_e32 v252, s100, v138
	v_add_u32_e32 v236, v252, v140
	v_add_u32_e32 v252, v252, v139
	s_waitcnt lgkmcnt(1)
	v_mfma_f32_32x32x16_bf16 v[114:129], v[146:149], v[150:153], v[114:129]
	ds_read_b128 v[232:235], v236
	s_add_i32 s10, s6, 1
	s_cmp_lg_u32 s6, 2
	s_cselect_b32 s6, s10, 0
	s_add_i32 s10, s54, 1
	s_cmp_lg_u32 s54, 2
	s_cselect_b32 s54, s10, 0
	v_mfma_f32_32x32x16_bf16 v[98:113], v[146:149], v[154:157], v[98:113]
	ds_read_b128 v[236:239], v236 offset:2048
	s_add_i32 s7, s7, -1
	v_lshl_add_u64 v[132:133], v[132:133], 0, s[56:57]
	s_cmp_eq_u32 s7, 0
	v_mfma_f32_32x32x16_bf16 v[66:81], v[146:149], v[158:161], v[66:81]
	ds_read_b128 v[240:243], v252 offset:8192
	v_mfma_f32_32x32x16_bf16 v[34:49], v[146:149], v[162:165], v[34:49]
	ds_read_b128 v[244:247], v252 offset:10240
	s_waitcnt lgkmcnt(4)
	v_mfma_f32_32x32x16_bf16 v[82:97], v[142:145], v[150:153], v[82:97]
	ds_read_b128 v[248:251], v252 offset:12288
	v_mfma_f32_32x32x16_bf16 v[50:65], v[142:145], v[154:157], v[50:65]
	ds_read_b128 v[252:255], v252 offset:14336
	v_mfma_f32_32x32x16_bf16 v[18:33], v[142:145], v[158:161], v[18:33]
	v_mfma_f32_32x32x16_bf16 v[2:17], v[142:145], v[162:165], v[2:17]
	s_cbranch_scc0 .LBB0_886
	s_waitcnt lgkmcnt(0)
	v_mfma_f32_32x32x16_bf16 v[82:97], v[232:235], v[240:243], v[82:97]
	v_mfma_f32_32x32x16_bf16 v[50:65], v[232:235], v[244:247], v[50:65]
	v_mfma_f32_32x32x16_bf16 v[18:33], v[232:235], v[248:251], v[18:33]
	v_mfma_f32_32x32x16_bf16 v[2:17], v[232:235], v[252:255], v[2:17]
	v_mfma_f32_32x32x16_bf16 v[114:129], v[236:239], v[240:243], v[114:129]
	v_mfma_f32_32x32x16_bf16 v[98:113], v[236:239], v[244:247], v[98:113]
	v_mfma_f32_32x32x16_bf16 v[66:81], v[236:239], v[248:251], v[66:81]
	v_mfma_f32_32x32x16_bf16 v[34:49], v[236:239], v[252:255], v[34:49]
	s_mul_i32 s7, s6, 0x6000
	s_add_i32 s10, s7, 0
	v_add_u32_e32 v0, s10, v137
	s_waitcnt vmcnt(6)
	v_add_u32_e32 v141, v0, v140
	s_waitcnt lgkmcnt(0)
	s_barrier
	ds_read_b128 v[130:133], v141
	ds_read_b128 v[142:145], v141 offset:2048
	v_add_u32_e32 v0, v0, v139
	ds_read_b128 v[146:149], v0 offset:8192
	ds_read_b128 v[150:153], v0 offset:10240
	ds_read_b128 v[154:157], v0 offset:12288
	ds_read_b128 v[158:161], v0 offset:14336
	s_waitcnt lgkmcnt(0)
	v_mfma_f32_32x32x16_bf16 v[82:97], v[130:133], v[146:149], v[82:97]
	v_add_u32_e32 v0, s10, v138
	v_add_u32_e32 v141, v0, v140
	v_add_u32_e32 v0, v0, v139
	s_addk_i32 s7, 0x6000
	s_cmp_lg_u32 s6, 2
	s_cselect_b32 s6, s7, 0
	s_add_i32 s6, s6, 0
	v_mfma_f32_32x32x16_bf16 v[114:129], v[142:145], v[146:149], v[114:129]
	v_readlane_b32 s12, v229, 29
	v_readlane_b32 s22, v229, 39
	v_readlane_b32 s23, v229, 40
	v_readlane_b32 s18, v229, 35
	v_readlane_b32 s19, v229, 36
	s_mov_b32 s58, 0
	v_readlane_b32 s13, v229, 30
	v_mfma_f32_32x32x16_bf16 v[50:65], v[130:133], v[150:153], v[50:65]
	v_readlane_b32 s14, v229, 31
	v_readlane_b32 s15, v229, 32
	v_readlane_b32 s16, v229, 33
	v_readlane_b32 s17, v229, 34
	v_readlane_b32 s20, v229, 37
	v_readlane_b32 s21, v229, 38
	v_readlane_b32 s24, v229, 41
	v_mfma_f32_32x32x16_bf16 v[18:33], v[130:133], v[154:157], v[18:33]
	v_readlane_b32 s25, v229, 42
	v_readlane_b32 s26, v229, 43
	v_readlane_b32 s27, v229, 44
	v_mfma_f32_32x32x16_bf16 v[2:17], v[130:133], v[158:161], v[2:17]
	v_mfma_f32_32x32x16_bf16 v[98:113], v[142:145], v[150:153], v[98:113]
	v_mfma_f32_32x32x16_bf16 v[66:81], v[142:145], v[154:157], v[66:81]
	v_mfma_f32_32x32x16_bf16 v[34:49], v[142:145], v[158:161], v[34:49]
	ds_read_b128 v[130:133], v141
	ds_read_b128 v[142:145], v141 offset:2048
	ds_read_b128 v[146:149], v0 offset:8192
	ds_read_b128 v[150:153], v0 offset:10240
	ds_read_b128 v[154:157], v0 offset:12288
	ds_read_b128 v[158:161], v0 offset:14336
	v_add_u32_e32 v0, s6, v137
	s_waitcnt vmcnt(0)
	v_add_u32_e32 v137, v0, v140
	s_waitcnt lgkmcnt(0)
	s_barrier
; DI unsigned pack2(float a, float b) { f32x2 v = {a, b}; bf16x2_t r = __builtin_convertvector(v, bf16x2_t); return __builtin_bit_cast(unsigned, r); }
; DI void gemm_tile(const Params& p, const GemmJob& j, int mt, int nt, char* smem) {
;     ...
;   for (int kt = 0; kt < nk; ++kt) {
;     if (kt + 1 < nk) asm volatile("s_waitcnt vmcnt(6)" ::: "memory"); else asm volatile("s_waitcnt vmcnt(0)" ::: "memory");
;     RAW_BARRIER();
;     if (kt + 2 < nk) glds(kt + 2, st2);
;     const char* sb = smem + st * GSTAGE;
; #pragma unroll
;     for (int ks = 0; ks < 2; ++ks) {
;       const int off = ks ? (o0 ^ 32) : o0;
;       bf16x8 wf[2], xf[4];
; #pragma unroll
;       for (int a = 0; a < 2; ++a) wf[a] = *(const bf16x8*)(sb + (64 * wn + 32 * a + r) * 64 + off);
; #pragma unroll
;       for (int b = 0; b < 4; ++b) xf[b] = *(const bf16x8*)(sb + 8192 + (128 * wt + 32 * b + r) * 64 + off);
; #pragma unroll
;       for (int a = 0; a < 2; ++a)
; #pragma unroll
;         for (int b = 0; b < 4; ++b) acc[a][b] = mfma32(wf[a], xf[b], acc[a][b]);
;     }
;     st = (st == 2) ? 0 : st + 1; st2 = (st2 == 2) ? 0 : st2 + 1;
;   }
;     ...
;     bf16_t* Cs = (bf16_t*)smem;
; #pragma unroll
;     for (int ni = 0; ni < 4; ++ni)
; #pragma unroll
;       for (int mi = 0; mi < 2; ++mi)
; #pragma unroll
;         for (int g = 0; g < 4; ++g)
;           *(u32x2*)(Cs + (128 * wt + 32 * ni + r) * 136 + 64 * wn + 32 * mi + 8 * g + 4 * h) =
;               (u32x2){pack2(acc[mi][ni][4 * g], acc[mi][ni][4 * g + 1]), pack2(acc[mi][ni][4 * g + 2], acc[mi][ni][4 * g + 3])};
;     __syncthreads();
; #pragma unroll 4
;     for (int q = 0; q < 16; ++q) {
;       const int idx = tid + 256 * q, row = idx >> 4, col = (idx & 15) * 8;
;       const u32x4 av = *(const u32x4*)(Cs + row * 136 + col);
;       bf16_t* xq = j.xbp + blk(t0 + row, n0 + col, NTOK);
;       float rv[8];
;       if (j.res) {
;         const f32x4 r0 = *(const f32x4*)(j.res + (size_t)(t0 + row) * 1024 + n0 + col), r1 = *(const f32x4*)(j.res + (size_t)(t0 + row) * 1024 + n0 + col + 4);
;         rv[0] = r0[0]; rv[1] = r0[1]; rv[2] = r0[2]; rv[3] = r0[3]; rv[4] = r1[0]; rv[5] = r1[1]; rv[6] = r1[2]; rv[7] = r1[3];
;       } else {
;         const u32x4 rb = *(const u32x4*)xq;
; #pragma unroll
;         for (int e = 0; e < 4; ++e) { rv[2 * e] = bflo(rb[e]); rv[2 * e + 1] = bfhi(rb[e]); }
;       }
;       float o[8]; float ss = 0.f;
; #pragma unroll
	s_waitcnt lgkmcnt(0)
	v_mfma_f32_32x32x16_bf16 v[82:97], v[130:133], v[146:149], v[82:97]
	v_add_u32_e32 v0, v0, v139
	v_mfma_f32_32x32x16_bf16 v[114:129], v[142:145], v[146:149], v[114:129]
	v_mfma_f32_32x32x16_bf16 v[50:65], v[130:133], v[150:153], v[50:65]
	v_mfma_f32_32x32x16_bf16 v[18:33], v[130:133], v[154:157], v[18:33]
	v_mfma_f32_32x32x16_bf16 v[2:17], v[130:133], v[158:161], v[2:17]
	v_mfma_f32_32x32x16_bf16 v[98:113], v[142:145], v[150:153], v[98:113]
	v_mfma_f32_32x32x16_bf16 v[66:81], v[142:145], v[154:157], v[66:81]
	v_mfma_f32_32x32x16_bf16 v[34:49], v[142:145], v[158:161], v[34:49]
	ds_read_b128 v[130:133], v137
	ds_read_b128 v[142:145], v137 offset:2048
	ds_read_b128 v[146:149], v0 offset:8192
	ds_read_b128 v[150:153], v0 offset:10240
	ds_read_b128 v[154:157], v0 offset:12288
	ds_read_b128 v[158:161], v0 offset:14336
	v_add_u32_e32 v0, s6, v138
	v_add_u32_e32 v137, v0, v140
	v_add_u32_e32 v0, v0, v139
	s_and_b32 s6, s31, 0xfffff80
	s_waitcnt lgkmcnt(0)
	v_mfma_f32_32x32x16_bf16 v[82:97], v[130:133], v[146:149], v[82:97]
	v_mfma_f32_32x32x16_bf16 v[114:129], v[142:145], v[146:149], v[114:129]
	v_mfma_f32_32x32x16_bf16 v[50:65], v[130:133], v[150:153], v[50:65]
	v_mfma_f32_32x32x16_bf16 v[18:33], v[130:133], v[154:157], v[18:33]
	v_mfma_f32_32x32x16_bf16 v[2:17], v[130:133], v[158:161], v[2:17]
	v_mfma_f32_32x32x16_bf16 v[98:113], v[142:145], v[150:153], v[98:113]
	v_mfma_f32_32x32x16_bf16 v[66:81], v[142:145], v[154:157], v[66:81]
	v_mfma_f32_32x32x16_bf16 v[34:49], v[142:145], v[158:161], v[34:49]
	ds_read_b128 v[130:133], v137
	ds_read_b128 v[140:143], v137 offset:2048
	ds_read_b128 v[144:147], v0 offset:8192
	ds_read_b128 v[148:151], v0 offset:10240
	ds_read_b128 v[152:155], v0 offset:12288
	ds_read_b128 v[156:159], v0 offset:14336
	v_or_b32_e32 v0, s6, v136
	s_lshl_b32 s6, s33, 7
	s_add_i32 s6, s6, 0
	v_mul_lo_u32 v0, v0, s0
	s_waitcnt vmcnt(0) lgkmcnt(0)
	v_mfma_f32_32x32x16_bf16 v[82:97], v[130:133], v[144:147], v[82:97]
	s_barrier
	v_mfma_f32_32x32x16_bf16 v[114:129], v[140:143], v[144:147], v[114:129]
	s_nop 9
	v_cvt_pk_bf16_f32 v82, v82, v83
	v_cvt_pk_bf16_f32 v83, v84, v85
	v_cvt_pk_bf16_f32 v84, v86, v87
	v_cvt_pk_bf16_f32 v85, v88, v89
	v_mfma_f32_32x32x16_bf16 v[50:65], v[130:133], v[148:151], v[50:65]
	v_mfma_f32_32x32x16_bf16 v[18:33], v[130:133], v[152:155], v[18:33]
	s_nop 10
	v_cvt_pk_bf16_f32 v50, v50, v51
	v_cvt_pk_bf16_f32 v51, v52, v53
	v_cvt_pk_bf16_f32 v52, v54, v55
	v_cvt_pk_bf16_f32 v53, v56, v57
	v_mfma_f32_32x32x16_bf16 v[2:17], v[130:133], v[156:159], v[2:17]
	v_lshlrev_b32_e32 v130, 3, v135
	v_add3_u32 v0, s6, v130, v0
	ds_write2_b64 v0, v[82:83], v[84:85] offset1:2
	v_cvt_pk_bf16_f32 v82, v90, v91
	v_cvt_pk_bf16_f32 v83, v92, v93
	v_cvt_pk_bf16_f32 v84, v94, v95
	v_cvt_pk_bf16_f32 v85, v96, v97
	v_mfma_f32_32x32x16_bf16 v[34:49], v[140:143], v[156:159], v[34:49]
	ds_write2_b64 v0, v[82:83], v[84:85] offset0:4 offset1:6
	v_cvt_pk_bf16_f32 v82, v114, v115
	v_cvt_pk_bf16_f32 v83, v116, v117
	v_cvt_pk_bf16_f32 v84, v118, v119
	v_cvt_pk_bf16_f32 v85, v120, v121
	ds_write2_b64 v0, v[82:83], v[84:85] offset0:8 offset1:10
	v_cvt_pk_bf16_f32 v82, v122, v123
	v_cvt_pk_bf16_f32 v83, v124, v125
	v_cvt_pk_bf16_f32 v84, v126, v127
	v_cvt_pk_bf16_f32 v85, v128, v129
	ds_write2_b64 v0, v[82:83], v[84:85] offset0:12 offset1:14
	v_add_u32_e32 v54, 0x2000, v0
	v_cvt_pk_bf16_f32 v18, v18, v19
	v_cvt_pk_bf16_f32 v19, v20, v21
	v_cvt_pk_bf16_f32 v20, v22, v23
	v_add_u32_e32 v22, 0x4000, v0
	v_cvt_pk_bf16_f32 v2, v2, v3
	v_cvt_pk_bf16_f32 v3, v4, v5
	v_cvt_pk_bf16_f32 v4, v6, v7
	v_cvt_pk_bf16_f32 v5, v8, v9
	v_add_u32_e32 v0, 0x6000, v0
	ds_write2_b64 v0, v[2:3], v[4:5] offset0:192 offset1:194
	v_cvt_pk_bf16_f32 v2, v10, v11
	v_cvt_pk_bf16_f32 v3, v12, v13
	v_cvt_pk_bf16_f32 v4, v14, v15
	v_cvt_pk_bf16_f32 v5, v16, v17
	ds_write2_b64 v0, v[2:3], v[4:5] offset0:196 offset1:198
	v_cvt_pk_bf16_f32 v2, v34, v35
	v_cvt_pk_bf16_f32 v3, v36, v37
	v_cvt_pk_bf16_f32 v4, v38, v39
	v_cvt_pk_bf16_f32 v5, v40, v41
	ds_write2_b64 v0, v[2:3], v[4:5] offset0:200 offset1:202
	v_cvt_pk_bf16_f32 v2, v42, v43
	v_cvt_pk_bf16_f32 v3, v44, v45
	v_cvt_pk_bf16_f32 v4, v46, v47
	v_cvt_pk_bf16_f32 v5, v48, v49
	ds_write2_b64 v0, v[2:3], v[4:5] offset0:204 offset1:206
	v_and_b32_e32 v2, 64, v202
	v_and_b32_e32 v3, 15, v134
	v_add_u32_e32 v2, 64, v2
	v_cmp_eq_u32_e32 vcc, 0, v3
	v_xor_b32_e32 v3, 1, v202
	v_cmp_lt_i32_e64 s[6:7], v3, v2
	v_mfma_f32_32x32x16_bf16 v[66:81], v[140:143], v[152:155], v[66:81]
	v_cvt_pk_bf16_f32 v21, v24, v25
	v_cndmask_b32_e64 v3, v202, v3, s[6:7]
	v_lshlrev_b32_e32 v15, 2, v3
	v_xor_b32_e32 v3, 2, v202
	v_cmp_lt_i32_e64 s[6:7], v3, v2
	v_lshlrev_b32_e32 v0, 3, v134
	v_and_b32_e32 v4, 0x78, v0
	v_cndmask_b32_e64 v3, v202, v3, s[6:7]
	v_lshlrev_b32_e32 v24, 2, v3
	v_xor_b32_e32 v3, 4, v202
	v_cmp_lt_i32_e64 s[6:7], v3, v2
	v_mfma_f32_32x32x16_bf16 v[98:113], v[140:143], v[148:151], v[98:113]
	v_or_b32_sdwa v0, s30, v4 dst_sel:WORD_1 dst_unused:UNUSED_PAD src0_sel:DWORD src1_sel:DWORD
	v_cndmask_b32_e64 v3, v202, v3, s[6:7]
	v_lshlrev_b32_e32 v25, 2, v3
	v_xor_b32_e32 v3, 8, v202
	v_cmp_lt_i32_e64 s[6:7], v3, v2
	v_and_b32_e32 v0, 0x3e00000, v0
	ds_write2_b64 v22, v[18:19], v[20:21] offset0:128 offset1:130
	v_cndmask_b32_e64 v2, v202, v3, s[6:7]
	v_cvt_pk_bf16_f32 v18, v26, v27
	v_cvt_pk_bf16_f32 v19, v28, v29
	v_cvt_pk_bf16_f32 v20, v30, v31
	v_cvt_pk_bf16_f32 v21, v32, v33
	v_lshlrev_b32_e32 v26, 2, v2
	v_lshl_add_u64 v[2:3], s[22:23], 0, v[0:1]
	v_lshlrev_b32_e32 v0, 4, v134
	s_lshl_b32 s6, s30, 2
	ds_write2_b64 v22, v[18:19], v[20:21] offset0:132 offset1:134
	v_cvt_pk_bf16_f32 v18, v66, v67
	v_cvt_pk_bf16_f32 v19, v68, v69
	v_cvt_pk_bf16_f32 v20, v70, v71
	v_cvt_pk_bf16_f32 v21, v72, v73
	v_and_b32_e32 v0, 48, v0
	s_add_u32 s6, s4, s6
	ds_write2_b64 v22, v[18:19], v[20:21] offset0:136 offset1:138
	v_cvt_pk_bf16_f32 v18, v74, v75
	v_cvt_pk_bf16_f32 v19, v76, v77
	v_cvt_pk_bf16_f32 v20, v78, v79
	v_cvt_pk_bf16_f32 v21, v80, v81
	v_lshl_add_u64 v[16:17], v[2:3], 0, v[0:1]
	s_addc_u32 s7, s5, 0
	v_lshlrev_b32_e32 v0, 2, v4
	ds_write2_b64 v54, v[50:51], v[52:53] offset0:64 offset1:66
	v_cvt_pk_bf16_f32 v50, v58, v59
	v_cvt_pk_bf16_f32 v51, v60, v61
	v_cvt_pk_bf16_f32 v52, v62, v63
	v_cvt_pk_bf16_f32 v53, v64, v65
	ds_write2_b64 v22, v[18:19], v[20:21] offset0:140 offset1:142
	v_lshl_add_u64 v[18:19], s[6:7], 0, v[0:1]
	s_and_b64 s[10:11], vcc, s[72:73]
	s_lshl_b32 s6, s29, 2
	ds_write2_b64 v54, v[50:51], v[52:53] offset0:68 offset1:70
	v_cvt_pk_bf16_f32 v50, v98, v99
	v_cvt_pk_bf16_f32 v51, v100, v101
	v_cvt_pk_bf16_f32 v52, v102, v103
	v_cvt_pk_bf16_f32 v53, v104, v105
	s_add_u32 s54, s18, s6
	ds_write2_b64 v54, v[50:51], v[52:53] offset0:72 offset1:74
	v_cvt_pk_bf16_f32 v50, v106, v107
	v_cvt_pk_bf16_f32 v51, v108, v109
	v_cvt_pk_bf16_f32 v52, v110, v111
	v_cvt_pk_bf16_f32 v53, v112, v113
	v_lshl_add_u32 v14, v4, 1, 0
	s_addc_u32 s55, s19, 0
	ds_write2_b64 v54, v[50:51], v[52:53] offset0:76 offset1:78
	s_waitcnt lgkmcnt(0)
	s_barrier
